# WKV scan: recurrence waves run at s_setprio 3 so the co-resident prep waves only take idle issue slots
# speedup vs baseline: 1.0121x; 1.0021x over previous
.LBB0_545:
	s_setprio 3
	s_mul_i32 s4, s93, 0x6000
	s_lshl_b32 s5, s93, 14
	v_add_u32_e32 v2, s4, v194
	v_add_u32_e32 v3, s4, v195
	v_add_u32_e32 v0, s5, v196
	ds_read_b128 v[24:27], v2 offset:16384
	ds_read_b64 v[44:45], v3 offset:12288
	ds_read_b128 v[36:39], v2 offset:8192
	ds_read_b128 v[28:31], v2 offset:4096
	ds_read_b128 v[32:35], v2 offset:20480
	ds_read_b128 v[40:43], v2 offset:0
	ds_read_b128 v[144:147], v2 offset:16640
	ds_read_b64 v[164:165], v3 offset:12544
	ds_read_b128 v[156:159], v2 offset:8448
	ds_read_b128 v[148:151], v2 offset:4352
	ds_read_b128 v[152:155], v2 offset:20736
	s_waitcnt lgkmcnt(5)
	v_pk_mul_f32 v[46:47], v[16:17], v[24:25] op_sel_hi:[1,0]
	v_pk_fma_f32 v[46:47], v[18:19], v[24:25], v[46:47] op_sel:[0,1,0] op_sel_hi:[1,1,1]
	v_pk_fma_f32 v[46:47], v[20:21], v[26:27], v[46:47] op_sel_hi:[1,0,1]
	v_pk_fma_f32 v[46:47], v[22:23], v[26:27], v[46:47] op_sel:[0,1,0] op_sel_hi:[1,1,1]
	ds_read_b128 v[160:163], v2 offset:256
	v_pk_mul_f32 v[168:169], v[44:45], v[36:37] op_sel_hi:[1,0]
	v_add_f32_dpp v48, v47, v46 quad_perm:[1,0,3,2] row_mask:0xf bank_mask:0xf bound_ctrl:1
	v_pk_mul_f32 v[170:171], v[44:45], v[36:37] op_sel:[0,1] op_sel_hi:[1,1]
	s_nop 0
	v_add_f32_dpp v48, v48, v48 quad_perm:[2,3,0,1] row_mask:0xf bank_mask:0xf bound_ctrl:1
	v_pk_mul_f32 v[172:173], v[44:45], v[38:39] op_sel_hi:[1,0]
	v_pk_mul_f32 v[174:175], v[44:45], v[38:39] op_sel:[0,1] op_sel_hi:[1,1]
	v_add_f32_dpp v48, v48, v48 row_ror:4 row_mask:0xf bank_mask:0xf bound_ctrl:1
	v_pk_fma_f32 v[168:169], v[16:17], v[28:29], v[168:169] op_sel_hi:[1,0,1]
	v_pk_fma_f32 v[170:171], v[18:19], v[28:29], v[170:171] op_sel:[0,1,0] op_sel_hi:[1,1,1]
	v_add_f32_dpp v48, v48, v48 row_ror:8 row_mask:0xf bank_mask:0xf bound_ctrl:1
	v_pk_fma_f32 v[172:173], v[20:21], v[30:31], v[172:173] op_sel_hi:[1,0,1]
	v_pk_fma_f32 v[174:175], v[22:23], v[30:31], v[174:175] op_sel:[0,1,0] op_sel_hi:[1,1,1]
	v_mov_b32_dpp v49, v48 quad_perm:[1,0,3,2] row_mask:0xf bank_mask:0xf bound_ctrl:1
	v_pk_fma_f32 v[16:17], v[48:49], v[32:33], v[168:169] op_sel_hi:[1,0,1] neg_lo:[0,1,0] neg_hi:[0,1,0]
	v_pk_fma_f32 v[18:19], v[48:49], v[32:33], v[170:171] op_sel:[0,1,0] op_sel_hi:[1,1,1] neg_lo:[0,1,0] neg_hi:[0,1,0]
	v_pk_fma_f32 v[20:21], v[48:49], v[34:35], v[172:173] op_sel_hi:[1,0,1] neg_lo:[0,1,0] neg_hi:[0,1,0]
	v_pk_fma_f32 v[22:23], v[48:49], v[34:35], v[174:175] op_sel:[0,1,0] op_sel_hi:[1,1,1] neg_lo:[0,1,0] neg_hi:[0,1,0]
	ds_read_b128 v[24:27], v2 offset:16896
	ds_read_b64 v[44:45], v3 offset:12800
	ds_read_b128 v[36:39], v2 offset:8704
	ds_read_b128 v[28:31], v2 offset:4608
	ds_read_b128 v[32:35], v2 offset:20992
	s_waitcnt lgkmcnt(5)
	v_pk_mul_f32 v[46:47], v[16:17], v[144:145] op_sel_hi:[1,0]
	v_pk_mul_f32 v[50:51], v[16:17], v[40:41] op_sel_hi:[1,0]
	v_pk_fma_f32 v[46:47], v[18:19], v[144:145], v[46:47] op_sel:[0,1,0] op_sel_hi:[1,1,1]
	v_pk_fma_f32 v[50:51], v[18:19], v[40:41], v[50:51] op_sel:[0,1,0] op_sel_hi:[1,1,1]
	v_pk_fma_f32 v[46:47], v[20:21], v[146:147], v[46:47] op_sel_hi:[1,0,1]
	v_pk_fma_f32 v[50:51], v[20:21], v[42:43], v[50:51] op_sel_hi:[1,0,1]
	v_pk_fma_f32 v[46:47], v[22:23], v[146:147], v[46:47] op_sel:[0,1,0] op_sel_hi:[1,1,1]
	v_pk_fma_f32 v[50:51], v[22:23], v[42:43], v[50:51] op_sel:[0,1,0] op_sel_hi:[1,1,1]
	ds_read_b128 v[40:43], v2 offset:512
	v_pk_mul_f32 v[168:169], v[164:165], v[156:157] op_sel_hi:[1,0]
	v_add_f32_dpp v48, v47, v46 quad_perm:[1,0,3,2] row_mask:0xf bank_mask:0xf bound_ctrl:1
	v_add_f32_dpp v52, v51, v50 quad_perm:[1,0,3,2] row_mask:0xf bank_mask:0xf bound_ctrl:1
	v_pk_mul_f32 v[170:171], v[164:165], v[156:157] op_sel:[0,1] op_sel_hi:[1,1]
	v_add_f32_dpp v48, v48, v48 quad_perm:[2,3,0,1] row_mask:0xf bank_mask:0xf bound_ctrl:1
	v_pk_mul_f32 v[172:173], v[164:165], v[158:159] op_sel_hi:[1,0]
	v_pk_mul_f32 v[174:175], v[164:165], v[158:159] op_sel:[0,1] op_sel_hi:[1,1]
	v_add_f32_dpp v48, v48, v48 row_ror:4 row_mask:0xf bank_mask:0xf bound_ctrl:1
	v_pk_fma_f32 v[168:169], v[16:17], v[148:149], v[168:169] op_sel_hi:[1,0,1]
	v_pk_fma_f32 v[170:171], v[18:19], v[148:149], v[170:171] op_sel:[0,1,0] op_sel_hi:[1,1,1]
	v_add_f32_dpp v48, v48, v48 row_ror:8 row_mask:0xf bank_mask:0xf bound_ctrl:1
	v_pk_fma_f32 v[172:173], v[20:21], v[150:151], v[172:173] op_sel_hi:[1,0,1]
	v_pk_fma_f32 v[174:175], v[22:23], v[150:151], v[174:175] op_sel:[0,1,0] op_sel_hi:[1,1,1]
	v_mov_b32_dpp v49, v48 quad_perm:[1,0,3,2] row_mask:0xf bank_mask:0xf bound_ctrl:1
	v_pk_fma_f32 v[16:17], v[48:49], v[152:153], v[168:169] op_sel_hi:[1,0,1] neg_lo:[0,1,0] neg_hi:[0,1,0]
	v_pk_fma_f32 v[18:19], v[48:49], v[152:153], v[170:171] op_sel:[0,1,0] op_sel_hi:[1,1,1] neg_lo:[0,1,0] neg_hi:[0,1,0]
	v_pk_fma_f32 v[20:21], v[48:49], v[154:155], v[172:173] op_sel_hi:[1,0,1] neg_lo:[0,1,0] neg_hi:[0,1,0]
	v_pk_fma_f32 v[22:23], v[48:49], v[154:155], v[174:175] op_sel:[0,1,0] op_sel_hi:[1,1,1] neg_lo:[0,1,0] neg_hi:[0,1,0]
	ds_read_b128 v[144:147], v2 offset:17152
	ds_read_b64 v[164:165], v3 offset:13056
	ds_read_b128 v[156:159], v2 offset:8960
	ds_read_b128 v[148:151], v2 offset:4864
	ds_read_b128 v[152:155], v2 offset:21248
	s_waitcnt lgkmcnt(5)
	v_pk_mul_f32 v[46:47], v[16:17], v[24:25] op_sel_hi:[1,0]
	v_pk_mul_f32 v[50:51], v[16:17], v[160:161] op_sel_hi:[1,0]
	v_pk_fma_f32 v[46:47], v[18:19], v[24:25], v[46:47] op_sel:[0,1,0] op_sel_hi:[1,1,1]
	v_pk_fma_f32 v[50:51], v[18:19], v[160:161], v[50:51] op_sel:[0,1,0] op_sel_hi:[1,1,1]
	v_pk_fma_f32 v[46:47], v[20:21], v[26:27], v[46:47] op_sel_hi:[1,0,1]
	v_pk_fma_f32 v[50:51], v[20:21], v[162:163], v[50:51] op_sel_hi:[1,0,1]
	v_pk_fma_f32 v[46:47], v[22:23], v[26:27], v[46:47] op_sel:[0,1,0] op_sel_hi:[1,1,1]
	v_pk_fma_f32 v[50:51], v[22:23], v[162:163], v[50:51] op_sel:[0,1,0] op_sel_hi:[1,1,1]
	ds_read_b128 v[160:163], v2 offset:768
	v_pk_mul_f32 v[168:169], v[44:45], v[36:37] op_sel_hi:[1,0]
	v_add_f32_dpp v48, v47, v46 quad_perm:[1,0,3,2] row_mask:0xf bank_mask:0xf bound_ctrl:1
	v_add_f32_dpp v53, v51, v50 quad_perm:[1,0,3,2] row_mask:0xf bank_mask:0xf bound_ctrl:1
	v_pk_mul_f32 v[170:171], v[44:45], v[36:37] op_sel:[0,1] op_sel_hi:[1,1]
	v_add_f32_dpp v48, v48, v48 quad_perm:[2,3,0,1] row_mask:0xf bank_mask:0xf bound_ctrl:1
	ds_write2st64_b32 v0, v52, v53 offset0:192 offset1:196
	v_pk_mul_f32 v[172:173], v[44:45], v[38:39] op_sel_hi:[1,0]
	v_pk_mul_f32 v[174:175], v[44:45], v[38:39] op_sel:[0,1] op_sel_hi:[1,1]
	v_add_f32_dpp v48, v48, v48 row_ror:4 row_mask:0xf bank_mask:0xf bound_ctrl:1
	v_pk_fma_f32 v[168:169], v[16:17], v[28:29], v[168:169] op_sel_hi:[1,0,1]
	v_pk_fma_f32 v[170:171], v[18:19], v[28:29], v[170:171] op_sel:[0,1,0] op_sel_hi:[1,1,1]
	v_add_f32_dpp v48, v48, v48 row_ror:8 row_mask:0xf bank_mask:0xf bound_ctrl:1
	v_pk_fma_f32 v[172:173], v[20:21], v[30:31], v[172:173] op_sel_hi:[1,0,1]
	v_pk_fma_f32 v[174:175], v[22:23], v[30:31], v[174:175] op_sel:[0,1,0] op_sel_hi:[1,1,1]
	v_mov_b32_dpp v49, v48 quad_perm:[1,0,3,2] row_mask:0xf bank_mask:0xf bound_ctrl:1
	v_pk_fma_f32 v[16:17], v[48:49], v[32:33], v[168:169] op_sel_hi:[1,0,1] neg_lo:[0,1,0] neg_hi:[0,1,0]
	v_pk_fma_f32 v[18:19], v[48:49], v[32:33], v[170:171] op_sel:[0,1,0] op_sel_hi:[1,1,1] neg_lo:[0,1,0] neg_hi:[0,1,0]
	v_pk_fma_f32 v[20:21], v[48:49], v[34:35], v[172:173] op_sel_hi:[1,0,1] neg_lo:[0,1,0] neg_hi:[0,1,0]
	v_pk_fma_f32 v[22:23], v[48:49], v[34:35], v[174:175] op_sel:[0,1,0] op_sel_hi:[1,1,1] neg_lo:[0,1,0] neg_hi:[0,1,0]
	ds_read_b128 v[24:27], v2 offset:17408
	ds_read_b64 v[44:45], v3 offset:13312
	ds_read_b128 v[36:39], v2 offset:9216
	ds_read_b128 v[28:31], v2 offset:5120
	ds_read_b128 v[32:35], v2 offset:21504
	s_waitcnt lgkmcnt(6)
	v_pk_mul_f32 v[46:47], v[16:17], v[144:145] op_sel_hi:[1,0]
	v_pk_mul_f32 v[50:51], v[16:17], v[40:41] op_sel_hi:[1,0]
	v_pk_fma_f32 v[46:47], v[18:19], v[144:145], v[46:47] op_sel:[0,1,0] op_sel_hi:[1,1,1]
	v_pk_fma_f32 v[50:51], v[18:19], v[40:41], v[50:51] op_sel:[0,1,0] op_sel_hi:[1,1,1]
	v_pk_fma_f32 v[46:47], v[20:21], v[146:147], v[46:47] op_sel_hi:[1,0,1]
	v_pk_fma_f32 v[50:51], v[20:21], v[42:43], v[50:51] op_sel_hi:[1,0,1]
	v_pk_fma_f32 v[46:47], v[22:23], v[146:147], v[46:47] op_sel:[0,1,0] op_sel_hi:[1,1,1]
	v_pk_fma_f32 v[50:51], v[22:23], v[42:43], v[50:51] op_sel:[0,1,0] op_sel_hi:[1,1,1]
	ds_read_b128 v[40:43], v2 offset:1024
	v_pk_mul_f32 v[168:169], v[164:165], v[156:157] op_sel_hi:[1,0]
	v_add_f32_dpp v48, v47, v46 quad_perm:[1,0,3,2] row_mask:0xf bank_mask:0xf bound_ctrl:1
	v_add_f32_dpp v52, v51, v50 quad_perm:[1,0,3,2] row_mask:0xf bank_mask:0xf bound_ctrl:1
	v_pk_mul_f32 v[170:171], v[164:165], v[156:157] op_sel:[0,1] op_sel_hi:[1,1]
	v_add_f32_dpp v48, v48, v48 quad_perm:[2,3,0,1] row_mask:0xf bank_mask:0xf bound_ctrl:1
	v_pk_mul_f32 v[172:173], v[164:165], v[158:159] op_sel_hi:[1,0]
	v_pk_mul_f32 v[174:175], v[164:165], v[158:159] op_sel:[0,1] op_sel_hi:[1,1]
	v_add_f32_dpp v48, v48, v48 row_ror:4 row_mask:0xf bank_mask:0xf bound_ctrl:1
	v_pk_fma_f32 v[168:169], v[16:17], v[148:149], v[168:169] op_sel_hi:[1,0,1]
	v_pk_fma_f32 v[170:171], v[18:19], v[148:149], v[170:171] op_sel:[0,1,0] op_sel_hi:[1,1,1]
	v_add_f32_dpp v48, v48, v48 row_ror:8 row_mask:0xf bank_mask:0xf bound_ctrl:1
	v_pk_fma_f32 v[172:173], v[20:21], v[150:151], v[172:173] op_sel_hi:[1,0,1]
	v_pk_fma_f32 v[174:175], v[22:23], v[150:151], v[174:175] op_sel:[0,1,0] op_sel_hi:[1,1,1]
	v_mov_b32_dpp v49, v48 quad_perm:[1,0,3,2] row_mask:0xf bank_mask:0xf bound_ctrl:1
	v_pk_fma_f32 v[16:17], v[48:49], v[152:153], v[168:169] op_sel_hi:[1,0,1] neg_lo:[0,1,0] neg_hi:[0,1,0]
	v_pk_fma_f32 v[18:19], v[48:49], v[152:153], v[170:171] op_sel:[0,1,0] op_sel_hi:[1,1,1] neg_lo:[0,1,0] neg_hi:[0,1,0]
	v_pk_fma_f32 v[20:21], v[48:49], v[154:155], v[172:173] op_sel_hi:[1,0,1] neg_lo:[0,1,0] neg_hi:[0,1,0]
	v_pk_fma_f32 v[22:23], v[48:49], v[154:155], v[174:175] op_sel:[0,1,0] op_sel_hi:[1,1,1] neg_lo:[0,1,0] neg_hi:[0,1,0]
	ds_read_b128 v[144:147], v2 offset:17664
	ds_read_b64 v[164:165], v3 offset:13568
	ds_read_b128 v[156:159], v2 offset:9472
	ds_read_b128 v[148:151], v2 offset:5376
	ds_read_b128 v[152:155], v2 offset:21760
	s_waitcnt lgkmcnt(5)
	v_pk_mul_f32 v[46:47], v[16:17], v[24:25] op_sel_hi:[1,0]
	v_pk_mul_f32 v[50:51], v[16:17], v[160:161] op_sel_hi:[1,0]
	v_pk_fma_f32 v[46:47], v[18:19], v[24:25], v[46:47] op_sel:[0,1,0] op_sel_hi:[1,1,1]
	v_pk_fma_f32 v[50:51], v[18:19], v[160:161], v[50:51] op_sel:[0,1,0] op_sel_hi:[1,1,1]
	v_pk_fma_f32 v[46:47], v[20:21], v[26:27], v[46:47] op_sel_hi:[1,0,1]
	v_pk_fma_f32 v[50:51], v[20:21], v[162:163], v[50:51] op_sel_hi:[1,0,1]
	v_pk_fma_f32 v[46:47], v[22:23], v[26:27], v[46:47] op_sel:[0,1,0] op_sel_hi:[1,1,1]
	v_pk_fma_f32 v[50:51], v[22:23], v[162:163], v[50:51] op_sel:[0,1,0] op_sel_hi:[1,1,1]
	ds_read_b128 v[160:163], v2 offset:1280
	v_pk_mul_f32 v[168:169], v[44:45], v[36:37] op_sel_hi:[1,0]
	v_add_f32_dpp v48, v47, v46 quad_perm:[1,0,3,2] row_mask:0xf bank_mask:0xf bound_ctrl:1
	v_add_f32_dpp v53, v51, v50 quad_perm:[1,0,3,2] row_mask:0xf bank_mask:0xf bound_ctrl:1
	v_pk_mul_f32 v[170:171], v[44:45], v[36:37] op_sel:[0,1] op_sel_hi:[1,1]
	v_add_f32_dpp v48, v48, v48 quad_perm:[2,3,0,1] row_mask:0xf bank_mask:0xf bound_ctrl:1
	ds_write2st64_b32 v0, v52, v53 offset0:200 offset1:204
	v_pk_mul_f32 v[172:173], v[44:45], v[38:39] op_sel_hi:[1,0]
	v_pk_mul_f32 v[174:175], v[44:45], v[38:39] op_sel:[0,1] op_sel_hi:[1,1]
	v_add_f32_dpp v48, v48, v48 row_ror:4 row_mask:0xf bank_mask:0xf bound_ctrl:1
	v_pk_fma_f32 v[168:169], v[16:17], v[28:29], v[168:169] op_sel_hi:[1,0,1]
	v_pk_fma_f32 v[170:171], v[18:19], v[28:29], v[170:171] op_sel:[0,1,0] op_sel_hi:[1,1,1]
	v_add_f32_dpp v48, v48, v48 row_ror:8 row_mask:0xf bank_mask:0xf bound_ctrl:1
	v_pk_fma_f32 v[172:173], v[20:21], v[30:31], v[172:173] op_sel_hi:[1,0,1]
	v_pk_fma_f32 v[174:175], v[22:23], v[30:31], v[174:175] op_sel:[0,1,0] op_sel_hi:[1,1,1]
	v_mov_b32_dpp v49, v48 quad_perm:[1,0,3,2] row_mask:0xf bank_mask:0xf bound_ctrl:1
	v_pk_fma_f32 v[16:17], v[48:49], v[32:33], v[168:169] op_sel_hi:[1,0,1] neg_lo:[0,1,0] neg_hi:[0,1,0]
	v_pk_fma_f32 v[18:19], v[48:49], v[32:33], v[170:171] op_sel:[0,1,0] op_sel_hi:[1,1,1] neg_lo:[0,1,0] neg_hi:[0,1,0]
	v_pk_fma_f32 v[20:21], v[48:49], v[34:35], v[172:173] op_sel_hi:[1,0,1] neg_lo:[0,1,0] neg_hi:[0,1,0]
	v_pk_fma_f32 v[22:23], v[48:49], v[34:35], v[174:175] op_sel:[0,1,0] op_sel_hi:[1,1,1] neg_lo:[0,1,0] neg_hi:[0,1,0]
	ds_read_b128 v[24:27], v2 offset:17920
	ds_read_b64 v[44:45], v3 offset:13824
	ds_read_b128 v[36:39], v2 offset:9728
	ds_read_b128 v[28:31], v2 offset:5632
	ds_read_b128 v[32:35], v2 offset:22016
	s_waitcnt lgkmcnt(6)
	v_pk_mul_f32 v[46:47], v[16:17], v[144:145] op_sel_hi:[1,0]
	v_pk_mul_f32 v[50:51], v[16:17], v[40:41] op_sel_hi:[1,0]
	v_pk_fma_f32 v[46:47], v[18:19], v[144:145], v[46:47] op_sel:[0,1,0] op_sel_hi:[1,1,1]
	v_pk_fma_f32 v[50:51], v[18:19], v[40:41], v[50:51] op_sel:[0,1,0] op_sel_hi:[1,1,1]
	v_pk_fma_f32 v[46:47], v[20:21], v[146:147], v[46:47] op_sel_hi:[1,0,1]
	v_pk_fma_f32 v[50:51], v[20:21], v[42:43], v[50:51] op_sel_hi:[1,0,1]
	v_pk_fma_f32 v[46:47], v[22:23], v[146:147], v[46:47] op_sel:[0,1,0] op_sel_hi:[1,1,1]
	v_pk_fma_f32 v[50:51], v[22:23], v[42:43], v[50:51] op_sel:[0,1,0] op_sel_hi:[1,1,1]
	ds_read_b128 v[40:43], v2 offset:1536
	v_pk_mul_f32 v[168:169], v[164:165], v[156:157] op_sel_hi:[1,0]
	v_add_f32_dpp v48, v47, v46 quad_perm:[1,0,3,2] row_mask:0xf bank_mask:0xf bound_ctrl:1
	v_add_f32_dpp v52, v51, v50 quad_perm:[1,0,3,2] row_mask:0xf bank_mask:0xf bound_ctrl:1
	v_pk_mul_f32 v[170:171], v[164:165], v[156:157] op_sel:[0,1] op_sel_hi:[1,1]
	v_add_f32_dpp v48, v48, v48 quad_perm:[2,3,0,1] row_mask:0xf bank_mask:0xf bound_ctrl:1
	v_pk_mul_f32 v[172:173], v[164:165], v[158:159] op_sel_hi:[1,0]
	v_pk_mul_f32 v[174:175], v[164:165], v[158:159] op_sel:[0,1] op_sel_hi:[1,1]
	v_add_f32_dpp v48, v48, v48 row_ror:4 row_mask:0xf bank_mask:0xf bound_ctrl:1
	v_pk_fma_f32 v[168:169], v[16:17], v[148:149], v[168:169] op_sel_hi:[1,0,1]
	v_pk_fma_f32 v[170:171], v[18:19], v[148:149], v[170:171] op_sel:[0,1,0] op_sel_hi:[1,1,1]
	v_add_f32_dpp v48, v48, v48 row_ror:8 row_mask:0xf bank_mask:0xf bound_ctrl:1
	v_pk_fma_f32 v[172:173], v[20:21], v[150:151], v[172:173] op_sel_hi:[1,0,1]
	v_pk_fma_f32 v[174:175], v[22:23], v[150:151], v[174:175] op_sel:[0,1,0] op_sel_hi:[1,1,1]
	v_mov_b32_dpp v49, v48 quad_perm:[1,0,3,2] row_mask:0xf bank_mask:0xf bound_ctrl:1
	v_pk_fma_f32 v[16:17], v[48:49], v[152:153], v[168:169] op_sel_hi:[1,0,1] neg_lo:[0,1,0] neg_hi:[0,1,0]
	v_pk_fma_f32 v[18:19], v[48:49], v[152:153], v[170:171] op_sel:[0,1,0] op_sel_hi:[1,1,1] neg_lo:[0,1,0] neg_hi:[0,1,0]
	v_pk_fma_f32 v[20:21], v[48:49], v[154:155], v[172:173] op_sel_hi:[1,0,1] neg_lo:[0,1,0] neg_hi:[0,1,0]
	v_pk_fma_f32 v[22:23], v[48:49], v[154:155], v[174:175] op_sel:[0,1,0] op_sel_hi:[1,1,1] neg_lo:[0,1,0] neg_hi:[0,1,0]
	ds_read_b128 v[144:147], v2 offset:18176
	ds_read_b64 v[164:165], v3 offset:14080
	ds_read_b128 v[156:159], v2 offset:9984
	ds_read_b128 v[148:151], v2 offset:5888
	ds_read_b128 v[152:155], v2 offset:22272
	s_waitcnt lgkmcnt(5)
	v_pk_mul_f32 v[46:47], v[16:17], v[24:25] op_sel_hi:[1,0]
	v_pk_mul_f32 v[50:51], v[16:17], v[160:161] op_sel_hi:[1,0]
	v_pk_fma_f32 v[46:47], v[18:19], v[24:25], v[46:47] op_sel:[0,1,0] op_sel_hi:[1,1,1]
	v_pk_fma_f32 v[50:51], v[18:19], v[160:161], v[50:51] op_sel:[0,1,0] op_sel_hi:[1,1,1]
	v_pk_fma_f32 v[46:47], v[20:21], v[26:27], v[46:47] op_sel_hi:[1,0,1]
	v_pk_fma_f32 v[50:51], v[20:21], v[162:163], v[50:51] op_sel_hi:[1,0,1]
	v_pk_fma_f32 v[46:47], v[22:23], v[26:27], v[46:47] op_sel:[0,1,0] op_sel_hi:[1,1,1]
	v_pk_fma_f32 v[50:51], v[22:23], v[162:163], v[50:51] op_sel:[0,1,0] op_sel_hi:[1,1,1]
	ds_read_b128 v[160:163], v2 offset:1792
	v_pk_mul_f32 v[168:169], v[44:45], v[36:37] op_sel_hi:[1,0]
	v_add_f32_dpp v48, v47, v46 quad_perm:[1,0,3,2] row_mask:0xf bank_mask:0xf bound_ctrl:1
	v_add_f32_dpp v53, v51, v50 quad_perm:[1,0,3,2] row_mask:0xf bank_mask:0xf bound_ctrl:1
	v_pk_mul_f32 v[170:171], v[44:45], v[36:37] op_sel:[0,1] op_sel_hi:[1,1]
	v_add_f32_dpp v48, v48, v48 quad_perm:[2,3,0,1] row_mask:0xf bank_mask:0xf bound_ctrl:1
	ds_write2st64_b32 v0, v52, v53 offset0:208 offset1:212
	v_pk_mul_f32 v[172:173], v[44:45], v[38:39] op_sel_hi:[1,0]
	v_pk_mul_f32 v[174:175], v[44:45], v[38:39] op_sel:[0,1] op_sel_hi:[1,1]
	v_add_f32_dpp v48, v48, v48 row_ror:4 row_mask:0xf bank_mask:0xf bound_ctrl:1
	v_pk_fma_f32 v[168:169], v[16:17], v[28:29], v[168:169] op_sel_hi:[1,0,1]
	v_pk_fma_f32 v[170:171], v[18:19], v[28:29], v[170:171] op_sel:[0,1,0] op_sel_hi:[1,1,1]
	v_add_f32_dpp v48, v48, v48 row_ror:8 row_mask:0xf bank_mask:0xf bound_ctrl:1
	v_pk_fma_f32 v[172:173], v[20:21], v[30:31], v[172:173] op_sel_hi:[1,0,1]
	v_pk_fma_f32 v[174:175], v[22:23], v[30:31], v[174:175] op_sel:[0,1,0] op_sel_hi:[1,1,1]
	v_mov_b32_dpp v49, v48 quad_perm:[1,0,3,2] row_mask:0xf bank_mask:0xf bound_ctrl:1
	v_pk_fma_f32 v[16:17], v[48:49], v[32:33], v[168:169] op_sel_hi:[1,0,1] neg_lo:[0,1,0] neg_hi:[0,1,0]
	v_pk_fma_f32 v[18:19], v[48:49], v[32:33], v[170:171] op_sel:[0,1,0] op_sel_hi:[1,1,1] neg_lo:[0,1,0] neg_hi:[0,1,0]
	v_pk_fma_f32 v[20:21], v[48:49], v[34:35], v[172:173] op_sel_hi:[1,0,1] neg_lo:[0,1,0] neg_hi:[0,1,0]
	v_pk_fma_f32 v[22:23], v[48:49], v[34:35], v[174:175] op_sel:[0,1,0] op_sel_hi:[1,1,1] neg_lo:[0,1,0] neg_hi:[0,1,0]
	ds_read_b128 v[24:27], v2 offset:18432
	ds_read_b64 v[44:45], v3 offset:14336
	ds_read_b128 v[36:39], v2 offset:10240
	ds_read_b128 v[28:31], v2 offset:6144
	ds_read_b128 v[32:35], v2 offset:22528
	s_waitcnt lgkmcnt(6)
	v_pk_mul_f32 v[46:47], v[16:17], v[144:145] op_sel_hi:[1,0]
	v_pk_mul_f32 v[50:51], v[16:17], v[40:41] op_sel_hi:[1,0]
	v_pk_fma_f32 v[46:47], v[18:19], v[144:145], v[46:47] op_sel:[0,1,0] op_sel_hi:[1,1,1]
	v_pk_fma_f32 v[50:51], v[18:19], v[40:41], v[50:51] op_sel:[0,1,0] op_sel_hi:[1,1,1]
	v_pk_fma_f32 v[46:47], v[20:21], v[146:147], v[46:47] op_sel_hi:[1,0,1]
	v_pk_fma_f32 v[50:51], v[20:21], v[42:43], v[50:51] op_sel_hi:[1,0,1]
	v_pk_fma_f32 v[46:47], v[22:23], v[146:147], v[46:47] op_sel:[0,1,0] op_sel_hi:[1,1,1]
	v_pk_fma_f32 v[50:51], v[22:23], v[42:43], v[50:51] op_sel:[0,1,0] op_sel_hi:[1,1,1]
	ds_read_b128 v[40:43], v2 offset:2048
	v_pk_mul_f32 v[168:169], v[164:165], v[156:157] op_sel_hi:[1,0]
	v_add_f32_dpp v48, v47, v46 quad_perm:[1,0,3,2] row_mask:0xf bank_mask:0xf bound_ctrl:1
	v_add_f32_dpp v52, v51, v50 quad_perm:[1,0,3,2] row_mask:0xf bank_mask:0xf bound_ctrl:1
	v_pk_mul_f32 v[170:171], v[164:165], v[156:157] op_sel:[0,1] op_sel_hi:[1,1]
	v_add_f32_dpp v48, v48, v48 quad_perm:[2,3,0,1] row_mask:0xf bank_mask:0xf bound_ctrl:1
	v_pk_mul_f32 v[172:173], v[164:165], v[158:159] op_sel_hi:[1,0]
	v_pk_mul_f32 v[174:175], v[164:165], v[158:159] op_sel:[0,1] op_sel_hi:[1,1]
	v_add_f32_dpp v48, v48, v48 row_ror:4 row_mask:0xf bank_mask:0xf bound_ctrl:1
	v_pk_fma_f32 v[168:169], v[16:17], v[148:149], v[168:169] op_sel_hi:[1,0,1]
	v_pk_fma_f32 v[170:171], v[18:19], v[148:149], v[170:171] op_sel:[0,1,0] op_sel_hi:[1,1,1]
	v_add_f32_dpp v48, v48, v48 row_ror:8 row_mask:0xf bank_mask:0xf bound_ctrl:1
	v_pk_fma_f32 v[172:173], v[20:21], v[150:151], v[172:173] op_sel_hi:[1,0,1]
	v_pk_fma_f32 v[174:175], v[22:23], v[150:151], v[174:175] op_sel:[0,1,0] op_sel_hi:[1,1,1]
	v_mov_b32_dpp v49, v48 quad_perm:[1,0,3,2] row_mask:0xf bank_mask:0xf bound_ctrl:1
	v_pk_fma_f32 v[16:17], v[48:49], v[152:153], v[168:169] op_sel_hi:[1,0,1] neg_lo:[0,1,0] neg_hi:[0,1,0]
	v_pk_fma_f32 v[18:19], v[48:49], v[152:153], v[170:171] op_sel:[0,1,0] op_sel_hi:[1,1,1] neg_lo:[0,1,0] neg_hi:[0,1,0]
	v_pk_fma_f32 v[20:21], v[48:49], v[154:155], v[172:173] op_sel_hi:[1,0,1] neg_lo:[0,1,0] neg_hi:[0,1,0]
	v_pk_fma_f32 v[22:23], v[48:49], v[154:155], v[174:175] op_sel:[0,1,0] op_sel_hi:[1,1,1] neg_lo:[0,1,0] neg_hi:[0,1,0]
	ds_read_b128 v[144:147], v2 offset:18688
	ds_read_b64 v[164:165], v3 offset:14592
	ds_read_b128 v[156:159], v2 offset:10496
	ds_read_b128 v[148:151], v2 offset:6400
	ds_read_b128 v[152:155], v2 offset:22784
	s_waitcnt lgkmcnt(5)
	v_pk_mul_f32 v[46:47], v[16:17], v[24:25] op_sel_hi:[1,0]
	v_pk_mul_f32 v[50:51], v[16:17], v[160:161] op_sel_hi:[1,0]
	v_pk_fma_f32 v[46:47], v[18:19], v[24:25], v[46:47] op_sel:[0,1,0] op_sel_hi:[1,1,1]
	v_pk_fma_f32 v[50:51], v[18:19], v[160:161], v[50:51] op_sel:[0,1,0] op_sel_hi:[1,1,1]
	v_pk_fma_f32 v[46:47], v[20:21], v[26:27], v[46:47] op_sel_hi:[1,0,1]
	v_pk_fma_f32 v[50:51], v[20:21], v[162:163], v[50:51] op_sel_hi:[1,0,1]
	v_pk_fma_f32 v[46:47], v[22:23], v[26:27], v[46:47] op_sel:[0,1,0] op_sel_hi:[1,1,1]
	v_pk_fma_f32 v[50:51], v[22:23], v[162:163], v[50:51] op_sel:[0,1,0] op_sel_hi:[1,1,1]
	ds_read_b128 v[160:163], v2 offset:2304
	v_pk_mul_f32 v[168:169], v[44:45], v[36:37] op_sel_hi:[1,0]
	v_add_f32_dpp v48, v47, v46 quad_perm:[1,0,3,2] row_mask:0xf bank_mask:0xf bound_ctrl:1
	v_add_f32_dpp v53, v51, v50 quad_perm:[1,0,3,2] row_mask:0xf bank_mask:0xf bound_ctrl:1
	v_pk_mul_f32 v[170:171], v[44:45], v[36:37] op_sel:[0,1] op_sel_hi:[1,1]
	v_add_f32_dpp v48, v48, v48 quad_perm:[2,3,0,1] row_mask:0xf bank_mask:0xf bound_ctrl:1
	ds_write2st64_b32 v0, v52, v53 offset0:216 offset1:220
	v_pk_mul_f32 v[172:173], v[44:45], v[38:39] op_sel_hi:[1,0]
	v_pk_mul_f32 v[174:175], v[44:45], v[38:39] op_sel:[0,1] op_sel_hi:[1,1]
	v_add_f32_dpp v48, v48, v48 row_ror:4 row_mask:0xf bank_mask:0xf bound_ctrl:1
	v_pk_fma_f32 v[168:169], v[16:17], v[28:29], v[168:169] op_sel_hi:[1,0,1]
	v_pk_fma_f32 v[170:171], v[18:19], v[28:29], v[170:171] op_sel:[0,1,0] op_sel_hi:[1,1,1]
	v_add_f32_dpp v48, v48, v48 row_ror:8 row_mask:0xf bank_mask:0xf bound_ctrl:1
	v_pk_fma_f32 v[172:173], v[20:21], v[30:31], v[172:173] op_sel_hi:[1,0,1]
	v_pk_fma_f32 v[174:175], v[22:23], v[30:31], v[174:175] op_sel:[0,1,0] op_sel_hi:[1,1,1]
	v_mov_b32_dpp v49, v48 quad_perm:[1,0,3,2] row_mask:0xf bank_mask:0xf bound_ctrl:1
	v_pk_fma_f32 v[16:17], v[48:49], v[32:33], v[168:169] op_sel_hi:[1,0,1] neg_lo:[0,1,0] neg_hi:[0,1,0]
	v_pk_fma_f32 v[18:19], v[48:49], v[32:33], v[170:171] op_sel:[0,1,0] op_sel_hi:[1,1,1] neg_lo:[0,1,0] neg_hi:[0,1,0]
	v_pk_fma_f32 v[20:21], v[48:49], v[34:35], v[172:173] op_sel_hi:[1,0,1] neg_lo:[0,1,0] neg_hi:[0,1,0]
	v_pk_fma_f32 v[22:23], v[48:49], v[34:35], v[174:175] op_sel:[0,1,0] op_sel_hi:[1,1,1] neg_lo:[0,1,0] neg_hi:[0,1,0]
	ds_read_b128 v[24:27], v2 offset:18944
	ds_read_b64 v[44:45], v3 offset:14848
	ds_read_b128 v[36:39], v2 offset:10752
	ds_read_b128 v[28:31], v2 offset:6656
	ds_read_b128 v[32:35], v2 offset:23040
	s_waitcnt lgkmcnt(6)
	v_pk_mul_f32 v[46:47], v[16:17], v[144:145] op_sel_hi:[1,0]
	v_pk_mul_f32 v[50:51], v[16:17], v[40:41] op_sel_hi:[1,0]
	v_pk_fma_f32 v[46:47], v[18:19], v[144:145], v[46:47] op_sel:[0,1,0] op_sel_hi:[1,1,1]
	v_pk_fma_f32 v[50:51], v[18:19], v[40:41], v[50:51] op_sel:[0,1,0] op_sel_hi:[1,1,1]
	v_pk_fma_f32 v[46:47], v[20:21], v[146:147], v[46:47] op_sel_hi:[1,0,1]
	v_pk_fma_f32 v[50:51], v[20:21], v[42:43], v[50:51] op_sel_hi:[1,0,1]
	v_pk_fma_f32 v[46:47], v[22:23], v[146:147], v[46:47] op_sel:[0,1,0] op_sel_hi:[1,1,1]
	v_pk_fma_f32 v[50:51], v[22:23], v[42:43], v[50:51] op_sel:[0,1,0] op_sel_hi:[1,1,1]
	ds_read_b128 v[40:43], v2 offset:2560
	v_pk_mul_f32 v[168:169], v[164:165], v[156:157] op_sel_hi:[1,0]
	v_add_f32_dpp v48, v47, v46 quad_perm:[1,0,3,2] row_mask:0xf bank_mask:0xf bound_ctrl:1
	v_add_f32_dpp v52, v51, v50 quad_perm:[1,0,3,2] row_mask:0xf bank_mask:0xf bound_ctrl:1
	v_pk_mul_f32 v[170:171], v[164:165], v[156:157] op_sel:[0,1] op_sel_hi:[1,1]
	v_add_f32_dpp v48, v48, v48 quad_perm:[2,3,0,1] row_mask:0xf bank_mask:0xf bound_ctrl:1
	v_pk_mul_f32 v[172:173], v[164:165], v[158:159] op_sel_hi:[1,0]
	v_pk_mul_f32 v[174:175], v[164:165], v[158:159] op_sel:[0,1] op_sel_hi:[1,1]
	v_add_f32_dpp v48, v48, v48 row_ror:4 row_mask:0xf bank_mask:0xf bound_ctrl:1
	v_pk_fma_f32 v[168:169], v[16:17], v[148:149], v[168:169] op_sel_hi:[1,0,1]
	v_pk_fma_f32 v[170:171], v[18:19], v[148:149], v[170:171] op_sel:[0,1,0] op_sel_hi:[1,1,1]
	v_add_f32_dpp v48, v48, v48 row_ror:8 row_mask:0xf bank_mask:0xf bound_ctrl:1
	v_pk_fma_f32 v[172:173], v[20:21], v[150:151], v[172:173] op_sel_hi:[1,0,1]
	v_pk_fma_f32 v[174:175], v[22:23], v[150:151], v[174:175] op_sel:[0,1,0] op_sel_hi:[1,1,1]
	v_mov_b32_dpp v49, v48 quad_perm:[1,0,3,2] row_mask:0xf bank_mask:0xf bound_ctrl:1
	v_pk_fma_f32 v[16:17], v[48:49], v[152:153], v[168:169] op_sel_hi:[1,0,1] neg_lo:[0,1,0] neg_hi:[0,1,0]
	v_pk_fma_f32 v[18:19], v[48:49], v[152:153], v[170:171] op_sel:[0,1,0] op_sel_hi:[1,1,1] neg_lo:[0,1,0] neg_hi:[0,1,0]
	v_pk_fma_f32 v[20:21], v[48:49], v[154:155], v[172:173] op_sel_hi:[1,0,1] neg_lo:[0,1,0] neg_hi:[0,1,0]
	v_pk_fma_f32 v[22:23], v[48:49], v[154:155], v[174:175] op_sel:[0,1,0] op_sel_hi:[1,1,1] neg_lo:[0,1,0] neg_hi:[0,1,0]
	ds_read_b128 v[144:147], v2 offset:19200
	ds_read_b64 v[164:165], v3 offset:15104
	ds_read_b128 v[156:159], v2 offset:11008
	ds_read_b128 v[148:151], v2 offset:6912
	ds_read_b128 v[152:155], v2 offset:23296
	s_waitcnt lgkmcnt(5)
	v_pk_mul_f32 v[46:47], v[16:17], v[24:25] op_sel_hi:[1,0]
	v_pk_mul_f32 v[50:51], v[16:17], v[160:161] op_sel_hi:[1,0]
	v_pk_fma_f32 v[46:47], v[18:19], v[24:25], v[46:47] op_sel:[0,1,0] op_sel_hi:[1,1,1]
	v_pk_fma_f32 v[50:51], v[18:19], v[160:161], v[50:51] op_sel:[0,1,0] op_sel_hi:[1,1,1]
	v_pk_fma_f32 v[46:47], v[20:21], v[26:27], v[46:47] op_sel_hi:[1,0,1]
	v_pk_fma_f32 v[50:51], v[20:21], v[162:163], v[50:51] op_sel_hi:[1,0,1]
	v_pk_fma_f32 v[46:47], v[22:23], v[26:27], v[46:47] op_sel:[0,1,0] op_sel_hi:[1,1,1]
	v_pk_fma_f32 v[50:51], v[22:23], v[162:163], v[50:51] op_sel:[0,1,0] op_sel_hi:[1,1,1]
	ds_read_b128 v[160:163], v2 offset:2816
	v_pk_mul_f32 v[168:169], v[44:45], v[36:37] op_sel_hi:[1,0]
	v_add_f32_dpp v48, v47, v46 quad_perm:[1,0,3,2] row_mask:0xf bank_mask:0xf bound_ctrl:1
	v_add_f32_dpp v53, v51, v50 quad_perm:[1,0,3,2] row_mask:0xf bank_mask:0xf bound_ctrl:1
	v_pk_mul_f32 v[170:171], v[44:45], v[36:37] op_sel:[0,1] op_sel_hi:[1,1]
	v_add_f32_dpp v48, v48, v48 quad_perm:[2,3,0,1] row_mask:0xf bank_mask:0xf bound_ctrl:1
	ds_write2st64_b32 v0, v52, v53 offset0:224 offset1:228
	v_pk_mul_f32 v[172:173], v[44:45], v[38:39] op_sel_hi:[1,0]
	v_pk_mul_f32 v[174:175], v[44:45], v[38:39] op_sel:[0,1] op_sel_hi:[1,1]
	v_add_f32_dpp v48, v48, v48 row_ror:4 row_mask:0xf bank_mask:0xf bound_ctrl:1
	v_pk_fma_f32 v[168:169], v[16:17], v[28:29], v[168:169] op_sel_hi:[1,0,1]
	v_pk_fma_f32 v[170:171], v[18:19], v[28:29], v[170:171] op_sel:[0,1,0] op_sel_hi:[1,1,1]
	v_add_f32_dpp v48, v48, v48 row_ror:8 row_mask:0xf bank_mask:0xf bound_ctrl:1
	v_pk_fma_f32 v[172:173], v[20:21], v[30:31], v[172:173] op_sel_hi:[1,0,1]
	v_pk_fma_f32 v[174:175], v[22:23], v[30:31], v[174:175] op_sel:[0,1,0] op_sel_hi:[1,1,1]
	v_mov_b32_dpp v49, v48 quad_perm:[1,0,3,2] row_mask:0xf bank_mask:0xf bound_ctrl:1
	v_pk_fma_f32 v[16:17], v[48:49], v[32:33], v[168:169] op_sel_hi:[1,0,1] neg_lo:[0,1,0] neg_hi:[0,1,0]
	v_pk_fma_f32 v[18:19], v[48:49], v[32:33], v[170:171] op_sel:[0,1,0] op_sel_hi:[1,1,1] neg_lo:[0,1,0] neg_hi:[0,1,0]
	v_pk_fma_f32 v[20:21], v[48:49], v[34:35], v[172:173] op_sel_hi:[1,0,1] neg_lo:[0,1,0] neg_hi:[0,1,0]
	v_pk_fma_f32 v[22:23], v[48:49], v[34:35], v[174:175] op_sel:[0,1,0] op_sel_hi:[1,1,1] neg_lo:[0,1,0] neg_hi:[0,1,0]
	ds_read_b128 v[24:27], v2 offset:19456
	ds_read_b64 v[44:45], v3 offset:15360
	ds_read_b128 v[36:39], v2 offset:11264
	ds_read_b128 v[28:31], v2 offset:7168
	ds_read_b128 v[32:35], v2 offset:23552
	s_waitcnt lgkmcnt(6)
	v_pk_mul_f32 v[46:47], v[16:17], v[144:145] op_sel_hi:[1,0]
	v_pk_mul_f32 v[50:51], v[16:17], v[40:41] op_sel_hi:[1,0]
	v_pk_fma_f32 v[46:47], v[18:19], v[144:145], v[46:47] op_sel:[0,1,0] op_sel_hi:[1,1,1]
	v_pk_fma_f32 v[50:51], v[18:19], v[40:41], v[50:51] op_sel:[0,1,0] op_sel_hi:[1,1,1]
	v_pk_fma_f32 v[46:47], v[20:21], v[146:147], v[46:47] op_sel_hi:[1,0,1]
	v_pk_fma_f32 v[50:51], v[20:21], v[42:43], v[50:51] op_sel_hi:[1,0,1]
	v_pk_fma_f32 v[46:47], v[22:23], v[146:147], v[46:47] op_sel:[0,1,0] op_sel_hi:[1,1,1]
	v_pk_fma_f32 v[50:51], v[22:23], v[42:43], v[50:51] op_sel:[0,1,0] op_sel_hi:[1,1,1]
	ds_read_b128 v[40:43], v2 offset:3072
	v_pk_mul_f32 v[168:169], v[164:165], v[156:157] op_sel_hi:[1,0]
	v_add_f32_dpp v48, v47, v46 quad_perm:[1,0,3,2] row_mask:0xf bank_mask:0xf bound_ctrl:1
	v_add_f32_dpp v52, v51, v50 quad_perm:[1,0,3,2] row_mask:0xf bank_mask:0xf bound_ctrl:1
	v_pk_mul_f32 v[170:171], v[164:165], v[156:157] op_sel:[0,1] op_sel_hi:[1,1]
	v_add_f32_dpp v48, v48, v48 quad_perm:[2,3,0,1] row_mask:0xf bank_mask:0xf bound_ctrl:1
	v_pk_mul_f32 v[172:173], v[164:165], v[158:159] op_sel_hi:[1,0]
	v_pk_mul_f32 v[174:175], v[164:165], v[158:159] op_sel:[0,1] op_sel_hi:[1,1]
	v_add_f32_dpp v48, v48, v48 row_ror:4 row_mask:0xf bank_mask:0xf bound_ctrl:1
	v_pk_fma_f32 v[168:169], v[16:17], v[148:149], v[168:169] op_sel_hi:[1,0,1]
	v_pk_fma_f32 v[170:171], v[18:19], v[148:149], v[170:171] op_sel:[0,1,0] op_sel_hi:[1,1,1]
	v_add_f32_dpp v48, v48, v48 row_ror:8 row_mask:0xf bank_mask:0xf bound_ctrl:1
	v_pk_fma_f32 v[172:173], v[20:21], v[150:151], v[172:173] op_sel_hi:[1,0,1]
	v_pk_fma_f32 v[174:175], v[22:23], v[150:151], v[174:175] op_sel:[0,1,0] op_sel_hi:[1,1,1]
	v_mov_b32_dpp v49, v48 quad_perm:[1,0,3,2] row_mask:0xf bank_mask:0xf bound_ctrl:1
	v_pk_fma_f32 v[16:17], v[48:49], v[152:153], v[168:169] op_sel_hi:[1,0,1] neg_lo:[0,1,0] neg_hi:[0,1,0]
	v_pk_fma_f32 v[18:19], v[48:49], v[152:153], v[170:171] op_sel:[0,1,0] op_sel_hi:[1,1,1] neg_lo:[0,1,0] neg_hi:[0,1,0]
	v_pk_fma_f32 v[20:21], v[48:49], v[154:155], v[172:173] op_sel_hi:[1,0,1] neg_lo:[0,1,0] neg_hi:[0,1,0]
	v_pk_fma_f32 v[22:23], v[48:49], v[154:155], v[174:175] op_sel:[0,1,0] op_sel_hi:[1,1,1] neg_lo:[0,1,0] neg_hi:[0,1,0]
	ds_read_b128 v[144:147], v2 offset:19712
	ds_read_b64 v[164:165], v3 offset:15616
	ds_read_b128 v[156:159], v2 offset:11520
	ds_read_b128 v[148:151], v2 offset:7424
	ds_read_b128 v[152:155], v2 offset:23808
	s_waitcnt lgkmcnt(5)
	v_pk_mul_f32 v[46:47], v[16:17], v[24:25] op_sel_hi:[1,0]
	v_pk_mul_f32 v[50:51], v[16:17], v[160:161] op_sel_hi:[1,0]
	v_pk_fma_f32 v[46:47], v[18:19], v[24:25], v[46:47] op_sel:[0,1,0] op_sel_hi:[1,1,1]
	v_pk_fma_f32 v[50:51], v[18:19], v[160:161], v[50:51] op_sel:[0,1,0] op_sel_hi:[1,1,1]
	v_pk_fma_f32 v[46:47], v[20:21], v[26:27], v[46:47] op_sel_hi:[1,0,1]
	v_pk_fma_f32 v[50:51], v[20:21], v[162:163], v[50:51] op_sel_hi:[1,0,1]
	v_pk_fma_f32 v[46:47], v[22:23], v[26:27], v[46:47] op_sel:[0,1,0] op_sel_hi:[1,1,1]
	v_pk_fma_f32 v[50:51], v[22:23], v[162:163], v[50:51] op_sel:[0,1,0] op_sel_hi:[1,1,1]
	ds_read_b128 v[160:163], v2 offset:3328
	v_pk_mul_f32 v[168:169], v[44:45], v[36:37] op_sel_hi:[1,0]
	v_add_f32_dpp v48, v47, v46 quad_perm:[1,0,3,2] row_mask:0xf bank_mask:0xf bound_ctrl:1
	v_add_f32_dpp v53, v51, v50 quad_perm:[1,0,3,2] row_mask:0xf bank_mask:0xf bound_ctrl:1
	v_pk_mul_f32 v[170:171], v[44:45], v[36:37] op_sel:[0,1] op_sel_hi:[1,1]
	v_add_f32_dpp v48, v48, v48 quad_perm:[2,3,0,1] row_mask:0xf bank_mask:0xf bound_ctrl:1
	ds_write2st64_b32 v0, v52, v53 offset0:232 offset1:236
	v_pk_mul_f32 v[172:173], v[44:45], v[38:39] op_sel_hi:[1,0]
	v_pk_mul_f32 v[174:175], v[44:45], v[38:39] op_sel:[0,1] op_sel_hi:[1,1]
	v_add_f32_dpp v48, v48, v48 row_ror:4 row_mask:0xf bank_mask:0xf bound_ctrl:1
	v_pk_fma_f32 v[168:169], v[16:17], v[28:29], v[168:169] op_sel_hi:[1,0,1]
	v_pk_fma_f32 v[170:171], v[18:19], v[28:29], v[170:171] op_sel:[0,1,0] op_sel_hi:[1,1,1]
	v_add_f32_dpp v48, v48, v48 row_ror:8 row_mask:0xf bank_mask:0xf bound_ctrl:1
	v_pk_fma_f32 v[172:173], v[20:21], v[30:31], v[172:173] op_sel_hi:[1,0,1]
	v_pk_fma_f32 v[174:175], v[22:23], v[30:31], v[174:175] op_sel:[0,1,0] op_sel_hi:[1,1,1]
	v_mov_b32_dpp v49, v48 quad_perm:[1,0,3,2] row_mask:0xf bank_mask:0xf bound_ctrl:1
	v_pk_fma_f32 v[16:17], v[48:49], v[32:33], v[168:169] op_sel_hi:[1,0,1] neg_lo:[0,1,0] neg_hi:[0,1,0]
	v_pk_fma_f32 v[18:19], v[48:49], v[32:33], v[170:171] op_sel:[0,1,0] op_sel_hi:[1,1,1] neg_lo:[0,1,0] neg_hi:[0,1,0]
	v_pk_fma_f32 v[20:21], v[48:49], v[34:35], v[172:173] op_sel_hi:[1,0,1] neg_lo:[0,1,0] neg_hi:[0,1,0]
	v_pk_fma_f32 v[22:23], v[48:49], v[34:35], v[174:175] op_sel:[0,1,0] op_sel_hi:[1,1,1] neg_lo:[0,1,0] neg_hi:[0,1,0]
	ds_read_b128 v[24:27], v2 offset:19968
	ds_read_b64 v[44:45], v3 offset:15872
	ds_read_b128 v[36:39], v2 offset:11776
	ds_read_b128 v[28:31], v2 offset:7680
	ds_read_b128 v[32:35], v2 offset:24064
	s_waitcnt lgkmcnt(6)
	v_pk_mul_f32 v[46:47], v[16:17], v[144:145] op_sel_hi:[1,0]
	v_pk_mul_f32 v[50:51], v[16:17], v[40:41] op_sel_hi:[1,0]
	v_pk_fma_f32 v[46:47], v[18:19], v[144:145], v[46:47] op_sel:[0,1,0] op_sel_hi:[1,1,1]
	v_pk_fma_f32 v[50:51], v[18:19], v[40:41], v[50:51] op_sel:[0,1,0] op_sel_hi:[1,1,1]
	v_pk_fma_f32 v[46:47], v[20:21], v[146:147], v[46:47] op_sel_hi:[1,0,1]
	v_pk_fma_f32 v[50:51], v[20:21], v[42:43], v[50:51] op_sel_hi:[1,0,1]
	v_pk_fma_f32 v[46:47], v[22:23], v[146:147], v[46:47] op_sel:[0,1,0] op_sel_hi:[1,1,1]
	v_pk_fma_f32 v[50:51], v[22:23], v[42:43], v[50:51] op_sel:[0,1,0] op_sel_hi:[1,1,1]
	ds_read_b128 v[40:43], v2 offset:3584
	v_pk_mul_f32 v[168:169], v[164:165], v[156:157] op_sel_hi:[1,0]
	v_add_f32_dpp v48, v47, v46 quad_perm:[1,0,3,2] row_mask:0xf bank_mask:0xf bound_ctrl:1
	v_add_f32_dpp v52, v51, v50 quad_perm:[1,0,3,2] row_mask:0xf bank_mask:0xf bound_ctrl:1
	v_pk_mul_f32 v[170:171], v[164:165], v[156:157] op_sel:[0,1] op_sel_hi:[1,1]
	v_add_f32_dpp v48, v48, v48 quad_perm:[2,3,0,1] row_mask:0xf bank_mask:0xf bound_ctrl:1
	v_pk_mul_f32 v[172:173], v[164:165], v[158:159] op_sel_hi:[1,0]
	v_pk_mul_f32 v[174:175], v[164:165], v[158:159] op_sel:[0,1] op_sel_hi:[1,1]
	v_add_f32_dpp v48, v48, v48 row_ror:4 row_mask:0xf bank_mask:0xf bound_ctrl:1
	v_pk_fma_f32 v[168:169], v[16:17], v[148:149], v[168:169] op_sel_hi:[1,0,1]
	v_pk_fma_f32 v[170:171], v[18:19], v[148:149], v[170:171] op_sel:[0,1,0] op_sel_hi:[1,1,1]
	v_add_f32_dpp v48, v48, v48 row_ror:8 row_mask:0xf bank_mask:0xf bound_ctrl:1
	v_pk_fma_f32 v[172:173], v[20:21], v[150:151], v[172:173] op_sel_hi:[1,0,1]
	v_pk_fma_f32 v[174:175], v[22:23], v[150:151], v[174:175] op_sel:[0,1,0] op_sel_hi:[1,1,1]
	v_mov_b32_dpp v49, v48 quad_perm:[1,0,3,2] row_mask:0xf bank_mask:0xf bound_ctrl:1
	v_pk_fma_f32 v[16:17], v[48:49], v[152:153], v[168:169] op_sel_hi:[1,0,1] neg_lo:[0,1,0] neg_hi:[0,1,0]
	v_pk_fma_f32 v[18:19], v[48:49], v[152:153], v[170:171] op_sel:[0,1,0] op_sel_hi:[1,1,1] neg_lo:[0,1,0] neg_hi:[0,1,0]
	v_pk_fma_f32 v[20:21], v[48:49], v[154:155], v[172:173] op_sel_hi:[1,0,1] neg_lo:[0,1,0] neg_hi:[0,1,0]
	v_pk_fma_f32 v[22:23], v[48:49], v[154:155], v[174:175] op_sel:[0,1,0] op_sel_hi:[1,1,1] neg_lo:[0,1,0] neg_hi:[0,1,0]
	ds_read_b128 v[144:147], v2 offset:20224
	ds_read_b64 v[164:165], v3 offset:16128
	ds_read_b128 v[156:159], v2 offset:12032
	ds_read_b128 v[148:151], v2 offset:7936
	ds_read_b128 v[152:155], v2 offset:24320
	s_waitcnt lgkmcnt(5)
	v_pk_mul_f32 v[46:47], v[16:17], v[24:25] op_sel_hi:[1,0]
	v_pk_mul_f32 v[50:51], v[16:17], v[160:161] op_sel_hi:[1,0]
	v_pk_fma_f32 v[46:47], v[18:19], v[24:25], v[46:47] op_sel:[0,1,0] op_sel_hi:[1,1,1]
	v_pk_fma_f32 v[50:51], v[18:19], v[160:161], v[50:51] op_sel:[0,1,0] op_sel_hi:[1,1,1]
	v_pk_fma_f32 v[46:47], v[20:21], v[26:27], v[46:47] op_sel_hi:[1,0,1]
	v_pk_fma_f32 v[50:51], v[20:21], v[162:163], v[50:51] op_sel_hi:[1,0,1]
	v_pk_fma_f32 v[46:47], v[22:23], v[26:27], v[46:47] op_sel:[0,1,0] op_sel_hi:[1,1,1]
	v_pk_fma_f32 v[50:51], v[22:23], v[162:163], v[50:51] op_sel:[0,1,0] op_sel_hi:[1,1,1]
	ds_read_b128 v[160:163], v2 offset:3840
	v_pk_mul_f32 v[168:169], v[44:45], v[36:37] op_sel_hi:[1,0]
	v_add_f32_dpp v48, v47, v46 quad_perm:[1,0,3,2] row_mask:0xf bank_mask:0xf bound_ctrl:1
	v_add_f32_dpp v53, v51, v50 quad_perm:[1,0,3,2] row_mask:0xf bank_mask:0xf bound_ctrl:1
	v_pk_mul_f32 v[170:171], v[44:45], v[36:37] op_sel:[0,1] op_sel_hi:[1,1]
	v_add_f32_dpp v48, v48, v48 quad_perm:[2,3,0,1] row_mask:0xf bank_mask:0xf bound_ctrl:1
	ds_write2st64_b32 v0, v52, v53 offset0:240 offset1:244
	v_pk_mul_f32 v[172:173], v[44:45], v[38:39] op_sel_hi:[1,0]
	v_pk_mul_f32 v[174:175], v[44:45], v[38:39] op_sel:[0,1] op_sel_hi:[1,1]
	v_add_f32_dpp v48, v48, v48 row_ror:4 row_mask:0xf bank_mask:0xf bound_ctrl:1
	v_pk_fma_f32 v[168:169], v[16:17], v[28:29], v[168:169] op_sel_hi:[1,0,1]
	v_pk_fma_f32 v[170:171], v[18:19], v[28:29], v[170:171] op_sel:[0,1,0] op_sel_hi:[1,1,1]
	v_add_f32_dpp v48, v48, v48 row_ror:8 row_mask:0xf bank_mask:0xf bound_ctrl:1
	v_pk_fma_f32 v[172:173], v[20:21], v[30:31], v[172:173] op_sel_hi:[1,0,1]
	v_pk_fma_f32 v[174:175], v[22:23], v[30:31], v[174:175] op_sel:[0,1,0] op_sel_hi:[1,1,1]
	v_mov_b32_dpp v49, v48 quad_perm:[1,0,3,2] row_mask:0xf bank_mask:0xf bound_ctrl:1
	v_pk_fma_f32 v[16:17], v[48:49], v[32:33], v[168:169] op_sel_hi:[1,0,1] neg_lo:[0,1,0] neg_hi:[0,1,0]
	v_pk_fma_f32 v[18:19], v[48:49], v[32:33], v[170:171] op_sel:[0,1,0] op_sel_hi:[1,1,1] neg_lo:[0,1,0] neg_hi:[0,1,0]
	v_pk_fma_f32 v[20:21], v[48:49], v[34:35], v[172:173] op_sel_hi:[1,0,1] neg_lo:[0,1,0] neg_hi:[0,1,0]
	v_pk_fma_f32 v[22:23], v[48:49], v[34:35], v[174:175] op_sel:[0,1,0] op_sel_hi:[1,1,1] neg_lo:[0,1,0] neg_hi:[0,1,0]
	s_waitcnt lgkmcnt(1)
	v_pk_mul_f32 v[46:47], v[16:17], v[144:145] op_sel_hi:[1,0]
	v_pk_mul_f32 v[50:51], v[16:17], v[40:41] op_sel_hi:[1,0]
	v_pk_fma_f32 v[46:47], v[18:19], v[144:145], v[46:47] op_sel:[0,1,0] op_sel_hi:[1,1,1]
	v_pk_fma_f32 v[50:51], v[18:19], v[40:41], v[50:51] op_sel:[0,1,0] op_sel_hi:[1,1,1]
	v_pk_fma_f32 v[46:47], v[20:21], v[146:147], v[46:47] op_sel_hi:[1,0,1]
	v_pk_fma_f32 v[50:51], v[20:21], v[42:43], v[50:51] op_sel_hi:[1,0,1]
	v_pk_fma_f32 v[46:47], v[22:23], v[146:147], v[46:47] op_sel:[0,1,0] op_sel_hi:[1,1,1]
	v_pk_fma_f32 v[50:51], v[22:23], v[42:43], v[50:51] op_sel:[0,1,0] op_sel_hi:[1,1,1]
	v_pk_mul_f32 v[168:169], v[164:165], v[156:157] op_sel_hi:[1,0]
	v_add_f32_dpp v48, v47, v46 quad_perm:[1,0,3,2] row_mask:0xf bank_mask:0xf bound_ctrl:1
	v_add_f32_dpp v52, v51, v50 quad_perm:[1,0,3,2] row_mask:0xf bank_mask:0xf bound_ctrl:1
	v_pk_mul_f32 v[170:171], v[164:165], v[156:157] op_sel:[0,1] op_sel_hi:[1,1]
	v_add_f32_dpp v48, v48, v48 quad_perm:[2,3,0,1] row_mask:0xf bank_mask:0xf bound_ctrl:1
	v_pk_mul_f32 v[172:173], v[164:165], v[158:159] op_sel_hi:[1,0]
	v_pk_mul_f32 v[174:175], v[164:165], v[158:159] op_sel:[0,1] op_sel_hi:[1,1]
	v_add_f32_dpp v48, v48, v48 row_ror:4 row_mask:0xf bank_mask:0xf bound_ctrl:1
	v_pk_fma_f32 v[168:169], v[16:17], v[148:149], v[168:169] op_sel_hi:[1,0,1]
	v_pk_fma_f32 v[170:171], v[18:19], v[148:149], v[170:171] op_sel:[0,1,0] op_sel_hi:[1,1,1]
	v_add_f32_dpp v48, v48, v48 row_ror:8 row_mask:0xf bank_mask:0xf bound_ctrl:1
	v_pk_fma_f32 v[172:173], v[20:21], v[150:151], v[172:173] op_sel_hi:[1,0,1]
	v_pk_fma_f32 v[174:175], v[22:23], v[150:151], v[174:175] op_sel:[0,1,0] op_sel_hi:[1,1,1]
	v_mov_b32_dpp v49, v48 quad_perm:[1,0,3,2] row_mask:0xf bank_mask:0xf bound_ctrl:1
	v_pk_fma_f32 v[16:17], v[48:49], v[152:153], v[168:169] op_sel_hi:[1,0,1] neg_lo:[0,1,0] neg_hi:[0,1,0]
	v_pk_fma_f32 v[18:19], v[48:49], v[152:153], v[170:171] op_sel:[0,1,0] op_sel_hi:[1,1,1] neg_lo:[0,1,0] neg_hi:[0,1,0]
	v_pk_fma_f32 v[20:21], v[48:49], v[154:155], v[172:173] op_sel_hi:[1,0,1] neg_lo:[0,1,0] neg_hi:[0,1,0]
	v_pk_fma_f32 v[22:23], v[48:49], v[154:155], v[174:175] op_sel:[0,1,0] op_sel_hi:[1,1,1] neg_lo:[0,1,0] neg_hi:[0,1,0]
	v_pk_mul_f32 v[50:51], v[16:17], v[160:161] op_sel_hi:[1,0]
	v_pk_fma_f32 v[50:51], v[18:19], v[160:161], v[50:51] op_sel:[0,1,0] op_sel_hi:[1,1,1]
	v_pk_fma_f32 v[50:51], v[20:21], v[162:163], v[50:51] op_sel_hi:[1,0,1]
	v_pk_fma_f32 v[50:51], v[22:23], v[162:163], v[50:51] op_sel:[0,1,0] op_sel_hi:[1,1,1]
	s_nop 1
	v_add_f32_dpp v53, v51, v50 quad_perm:[1,0,3,2] row_mask:0xf bank_mask:0xf bound_ctrl:1
	ds_write2st64_b32 v0, v52, v53 offset0:248 offset1:252
	s_setprio 0
